# v28 + norm2 of groups 0..2 rows moved into the idle workgroups of the last group's branch-projection phase
# speedup vs baseline: 1.0339x; 1.0063x over previous
; #define BIDX bid_opaque()
; #define GDIM gdim_opaque()
; template <int RB> DI void norm_rows(float* X, const f32x4 (&gv)[4], bf16_t* XN, const float* wsm, float* SM, int row0, int lane, const float* part) {
;     ...
;         const int row = row0 + r; const f32x4* xr = (const f32x4*)(X + (size_t)row * D); float ss = 0.f;
; #pragma unroll
;         for (int j = 0; j < 4; ++j) v[r][j] = xr[lane + 64 * j];
; DI void norm_phase(float* X, const float* gain, bf16_t* XN, const float* wsm, float* SM, int wave, int lane, const float* part = nullptr) {
;     const int gw = BIDX * 8 + wave, NGW = GDIM * 8;
;     f32x4 gv[4];
; #pragma unroll
;     for (int j = 0; j < 4; ++j) gv[j] = ((const f32x4*)gain)[lane + 64 * j];
;     if (wsm) { for (int row0 = gw * 4; row0 < MTOT; row0 += NGW * 4) norm_rows<4>(X, gv, XN, wsm, SM, row0, lane, part); }
;     else { for (int row = gw; row < MTOT; row += NGW) norm_rows<1>(X, gv, XN, nullptr, nullptr, row, lane, part); }
.LBB0_196:
	s_and_b64 vcc, exec, s[4:5]
	s_cbranch_vccz .LBB0_200
	s_lshl_b32 s98, s92, 3
	s_mov_b32 s99, 0
	s_mov_b32 s100, 0x82ff
	s_cmp_lg_u32 s92, 0x100
	s_cbranch_scc1 .Ln2_go
	s_mov_b32 s99, 0x6300
.Ln2_go:
	s_waitcnt vmcnt(0)
	v_mov_b32_e32 v0, v228
	v_mov_b32_e32 v1, v228
	s_nop 0
	v_readfirstlane_b32 s0, v1
	s_ashr_i32 s1, s0, 6
	s_mov_b32 s0, s82
	s_lshl_b32 s2, s0, 3
	s_add_i32 s4, s2, s1
	s_add_i32 s4, s4, s99
	s_mov_b32 s0, s92
	s_cmp_gt_i32 s4, s100
	s_cbranch_scc1 .LBB0_200
	s_load_dwordx2 s[2:3], s[18:19], 0xc8
	s_load_dwordx2 s[6:7], s[18:19], 0xf0
	s_lshl_b32 s10, s96, 10
	s_ashr_i32 s11, s10, 31
	s_lshl_b64 s[10:11], s[10:11], 2
	v_and_b32_e32 v16, 63, v0
	s_waitcnt lgkmcnt(0)
	s_add_u32 s2, s2, s10
	s_addc_u32 s3, s3, s11
	v_lshlrev_b32_e32 v17, 4, v16
	global_load_dwordx4 v[0:3], v17, s[2:3]
	global_load_dwordx4 v[4:7], v17, s[2:3] offset:1024
	global_load_dwordx4 v[8:11], v17, s[2:3] offset:2048
	global_load_dwordx4 v[12:15], v17, s[2:3] offset:3072
	s_ashr_i32 s5, s4, 31
	s_mov_b32 s16, s98
	s_lshl_b64 s[0:1], s[4:5], 11
	v_lshl_or_b32 v28, v16, 3, s0
	v_mov_b32_e32 v29, s1
	s_ashr_i32 s17, s16, 31
	s_lshl_b64 s[0:1], s[4:5], 12
	s_lshl_b64 s[38:39], s[16:17], 11
	v_or_b32_e32 v30, s0, v17
	v_mov_b32_e32 v31, s1
	s_lshl_b64 s[40:41], s[16:17], 12
	v_lshl_add_u64 v[128:129], s[6:7], 0, v[30:31]
	global_load_dwordx4 v[112:115], v[128:129], off
	global_load_dwordx4 v[116:119], v[128:129], off offset:1024
	global_load_dwordx4 v[120:123], v[128:129], off offset:2048
	global_load_dwordx4 v[124:127], v[128:129], off offset:3072
	v_lshl_add_u64 v[30:31], v[30:31], 0, s[40:41]
	s_waitcnt vmcnt(0)
	s_branch .Ln2_in

; __device__ __forceinline__ unsigned cvt_pk_bf16(float lo, float hi) { const f32x2_cv v = {lo, hi}; const bf16x2_cv b = __builtin_convertvector(v, bf16x2_cv); return __builtin_bit_cast(unsigned, b); }
; template <int RB> DI void norm_rows(float* X, const f32x4 (&gv)[4], bf16_t* XN, const float* wsm, float* SM, int row0, int lane, const float* part) {
;     ...
;         const int row = row0 + r; const f32x4* xr = (const f32x4*)(X + (size_t)row * D); float ss = 0.f;
; #pragma unroll
;         for (int j = 0; j < 4; ++j) v[r][j] = xr[lane + 64 * j];
;         if (part && row >= MMAIN) {
; #pragma unroll 1
;             for (int kh = 0; kh < NKSL; ++kh) { const f32x4* pr = (const f32x4*)(part + ((size_t)kh * (MTOT - MMAIN) + (row - MMAIN)) * 1024);
; #pragma unroll
;                 for (int j = 0; j < 4; ++j) v[r][j] += pr[lane + 64 * j]; }
; #pragma unroll
;             for (int j = 0; j < 4; ++j) ((f32x4*)(X + (size_t)row * D))[lane + 64 * j] = v[r][j];
;         }
; #pragma unroll
;         for (int j = 0; j < 4; ++j) ss += (v[r][j][0] * v[r][j][0] + v[r][j][1] * v[r][j][1]) + (v[r][j][2] * v[r][j][2] + v[r][j][3] * v[r][j][3]);
;         const float rs = rsqrtf(wave_sum(ss) * (1.f / D) + EPS);
;         u32x2* o = (u32x2*)(XN + (size_t)row * D);
; #pragma unroll
;         for (int j = 0; j < 4; ++j) { v[r][j] = v[r][j] * rs * gv[j]; u32x2 w; w.x = cvt_pk_bf16(v[r][j][0], v[r][j][1]); w.y = cvt_pk_bf16(v[r][j][2], v[r][j][3]); o[lane + 64 * j] = w; }
.Ln2_in:
	v_mov_b64_e32 v[34:35], v[112:113]
	v_mov_b64_e32 v[36:37], v[114:115]
	v_mov_b64_e32 v[24:25], v[116:117]
	v_mov_b64_e32 v[26:27], v[118:119]
	v_mov_b64_e32 v[20:21], v[120:121]
	v_mov_b64_e32 v[22:23], v[122:123]
	v_mov_b64_e32 v[16:17], v[124:125]
	v_mov_b64_e32 v[18:19], v[126:127]
	v_lshl_add_u64 v[128:129], s[6:7], 0, v[30:31]
	global_load_dwordx4 v[112:115], v[128:129], off
	global_load_dwordx4 v[116:119], v[128:129], off offset:1024
	global_load_dwordx4 v[120:123], v[128:129], off offset:2048
	global_load_dwordx4 v[124:127], v[128:129], off offset:3072
	v_lshl_add_u64 v[30:31], v[30:31], 0, s[40:41]
	s_add_i32 s4, s4, s16
	s_cmp_gt_i32 s4, s100
	v_pk_mul_f32 v[38:39], v[36:37], v[36:37]
	v_pk_mul_f32 v[40:41], v[34:35], v[34:35]
	v_mul_f32_e32 v32, v20, v20
	v_pk_mov_b32 v[42:43], v[40:41], v[38:39] op_sel:[1,0]
	v_mov_b32_e32 v41, v39
	v_pk_add_f32 v[38:39], v[42:43], v[40:41]
	v_pk_mul_f32 v[40:41], v[26:27], v[26:27]
	v_pk_mul_f32 v[42:43], v[24:25], v[24:25]
	v_pk_add_f32 v[38:39], v[38:39], v[38:39] op_sel_hi:[0,1]
	v_pk_mov_b32 v[44:45], v[42:43], v[40:41] op_sel:[1,0]
	v_mov_b32_e32 v43, v41
	v_pk_add_f32 v[40:41], v[44:45], v[42:43]
	v_pk_fma_f32 v[42:43], v[20:21], v[20:21], v[32:33] op_sel_hi:[1,1,0]
	v_mul_f32_e32 v32, v22, v22
	v_pk_add_f32 v[40:41], v[40:41], v[40:41] op_sel_hi:[0,1]
	v_pk_fma_f32 v[44:45], v[22:23], v[22:23], v[32:33] op_sel_hi:[1,1,0]
	v_mul_f32_e32 v42, v16, v16
	v_mul_f32_e32 v44, v17, v17
	v_mul_f32_e32 v38, v18, v18
	v_mul_f32_e32 v40, v19, v19
	v_pk_add_f32 v[42:43], v[42:43], v[44:45]
	v_pk_add_f32 v[38:39], v[38:39], v[40:41]
	s_nop 0
	v_pk_add_f32 v[38:39], v[42:43], v[38:39]
	s_nop 0
	v_add_f32_e32 v32, v38, v39
	s_nop 1
	v_add_f32_dpp v32, v32, v32 quad_perm:[1,0,3,2] row_mask:0xf bank_mask:0xf bound_ctrl:1
	s_nop 1
	v_add_f32_dpp v32, v32, v32 quad_perm:[2,3,0,1] row_mask:0xf bank_mask:0xf bound_ctrl:1
	s_nop 1
	v_add_f32_dpp v32, v32, v32 row_half_mirror row_mask:0xf bank_mask:0xf bound_ctrl:1
	s_nop 1
	v_add_f32_dpp v32, v32, v32 row_mirror row_mask:0xf bank_mask:0xf bound_ctrl:1
	s_nop 0
	v_readlane_b32 s2, v32, 16
	v_readlane_b32 s3, v32, 48
	v_readlane_b32 s0, v32, 0
	v_readlane_b32 s1, v32, 32
	v_mov_b32_e32 v38, s2
	v_mov_b32_e32 v39, s3
	v_pk_add_f32 v[38:39], s[0:1], v[38:39]
	s_mov_b32 s0, 0x8300000
	v_add_f32_e32 v32, v38, v39
	v_fmamk_f32 v32, v32, 0x3a800000, v229
	v_cmp_gt_f32_e32 vcc, s81, v32
	v_mul_f32_e32 v38, 0x4b800000, v32
	s_nop 0
	v_cndmask_b32_e32 v32, v32, v38, vcc
	v_rsq_f32_e32 v32, v32
	s_nop 0
	v_mul_f32_e32 v38, 0x45800000, v32
	v_cndmask_b32_e32 v32, v32, v38, vcc
	v_pk_mul_f32 v[34:35], v[34:35], v[32:33] op_sel_hi:[1,0]
	v_pk_mul_f32 v[36:37], v[36:37], v[32:33] op_sel_hi:[1,0]
	v_pk_mul_f32 v[34:35], v[0:1], v[34:35]
	v_pk_mul_f32 v[36:37], v[2:3], v[36:37]
	v_cvt_pk_bf16_f32 v34, v34, v35
	v_cvt_pk_bf16_f32 v35, v36, v37
	v_lshl_add_u64 v[36:37], s[6:7], 0, v[28:29]
	v_pk_mul_f32 v[24:25], v[24:25], v[32:33] op_sel_hi:[1,0]
	v_pk_mul_f32 v[26:27], v[26:27], v[32:33] op_sel_hi:[1,0]
	v_pk_mul_f32 v[20:21], v[20:21], v[32:33] op_sel_hi:[1,0]
	v_pk_mul_f32 v[22:23], v[22:23], v[32:33] op_sel_hi:[1,0]
	v_pk_mul_f32 v[16:17], v[16:17], v[32:33] op_sel_hi:[1,0]
	v_pk_mul_f32 v[18:19], v[18:19], v[32:33] op_sel_hi:[1,0]
	v_add_co_u32_e32 v36, vcc, s0, v36
	v_pk_mul_f32 v[26:27], v[6:7], v[26:27]
	v_pk_mul_f32 v[24:25], v[4:5], v[24:25]
	v_pk_mul_f32 v[22:23], v[10:11], v[22:23]
	v_pk_mul_f32 v[20:21], v[8:9], v[20:21]
	v_pk_mul_f32 v[18:19], v[14:15], v[18:19]
	v_pk_mul_f32 v[16:17], v[12:13], v[16:17]
	v_addc_co_u32_e32 v37, vcc, 0, v37, vcc
	v_cvt_pk_bf16_f32 v24, v24, v25
	v_cvt_pk_bf16_f32 v25, v26, v27
	v_cvt_pk_bf16_f32 v20, v20, v21
	v_cvt_pk_bf16_f32 v21, v22, v23
	v_cvt_pk_bf16_f32 v16, v16, v17
	v_cvt_pk_bf16_f32 v17, v18, v19
	v_lshl_add_u64 v[28:29], v[28:29], 0, s[38:39]
	global_store_dwordx2 v[36:37], v[34:35], off
	global_store_dwordx2 v[36:37], v[24:25], off offset:512
	global_store_dwordx2 v[36:37], v[20:21], off offset:1024
	global_store_dwordx2 v[36:37], v[16:17], off offset:1536
	s_cbranch_scc0 .LBB0_199

; #define TIDV tid_opaque()
; #define BIDX bid_opaque()
; #define GDIM gdim_opaque()
; template <int KIND> DI void run_phase(PARAMS P, int l, int g) {
;     ...
;     else if constexpr (KIND == 6) {
;         pg8::Gemm gm{(const bf16_t*)((unsigned char*)P.out + DS_OB), wl + WL_WBR, gr, D, 512};
;         BrOrder S; S.S.init(gr, D, GDIM, BIDX);
;         EpiBr E{gb + (size_t)CP_ZG * G0ROWS, (float*)((unsigned char*)P.out + DS_MIXF), (bf16_t*)((unsigned char*)P.out + DS_MIXB)};
;         pg8::gemm_phase<EpiBr, BrOrder, true, true>(TIDV, lds, gm, S, E); }
;     ...
;     else if constexpr (KIND == 8) norm_phase(X, P.in[25] + l * D, XN, nullptr, nullptr, wave, lane);
.LBB0_395:
	s_and_b64 vcc, exec, s[4:5]
	s_cbranch_vccz .LBB0_456
	s_cmp_lg_u32 s92, 0x100
	s_cbranch_scc1 .Lk6_normal
	s_cmp_eq_u32 s34, 3
	s_cbranch_scc1 .Lk6_g3
	s_movk_i32 s99, 0x80
	s_cmp_eq_u32 s34, 0
	s_cselect_b32 s99, 0x8c, s99
	s_cmp_lt_u32 s82, s99
	s_cbranch_scc1 .Lk6_normal
	s_branch .Lk7_entry
.Lk6_g3:
	s_cmp_lt_u32 s82, 0x80
	s_cbranch_scc1 .Lk6_normal
	s_movk_i32 s98, 0x400
	s_mov_b32 s99, 0xfffffc00
	s_mov_b32 s100, 0x62ff
	s_branch .Ln2_go
